# P3 EpiQ rope epilogue: next rope-table load issued before the step's two dword stores; waits relaxed to vmcnt(2)
# speedup vs baseline: 1.0305x; 1.0064x over previous
.LBB0_662:
	s_lshl_b32 s31, s28, 24
	v_lshl_or_b32 v130, s29, 6, v131
	s_sext_i32_i8 s62, s28
	s_lshl_b32 s30, s30, 8
	s_lshl_b32 s63, s62, 8
	s_ashr_i32 s28, s31, 24
	v_add_u32_e32 v143, s30, v130
	s_cmp_lt_i32 s28, 4
	v_lshlrev_b32_e32 v133, 2, v128
	s_mov_b64 s[28:29], -1
	v_add_u32_e32 v134, 0xffffe000, v143
	v_add_u32_e32 v128, 0xffffe010, v143
	v_add_u32_e32 v132, 0xffffe020, v143
	v_add_u32_e32 v130, 0xffffe030, v143
	s_mov_b32 s84, s34
	s_cbranch_scc1 .LBB0_664
	v_and_b32_e32 v135, 0xfcf, v143
	v_or_b32_e32 v145, 0x1000, v131
	v_cmp_gt_i32_e32 vcc, s33, v143
	v_bitop3_b32 v136, v133, 44, s72 bitop3:0xc8
	s_add_i32 s28, s63, s61
	v_cndmask_b32_e32 v135, v145, v135, vcc
	v_lshlrev_b32_e32 v144, 6, v135
	v_or_b32_e32 v135, v144, v136
	v_lshlrev_b32_e32 v166, 2, v135
	global_load_dwordx4 v[146:149], v166, s[16:17]
	v_mov_b64_e32 v[140:141], s[0:1]
	s_add_i32 s30, s28, 0xfffffc00
	v_mad_i64_i32 v[156:157], s[28:29], v143, s45, v[140:141]
	v_lshrrev_b32_e32 v150, 5, v134
	v_mov_b32_e32 v151, v129
	s_ashr_i32 s29, s30, 6
	v_lshlrev_b64 v[150:151], 8, v[150:151]
	s_lshl_b32 s28, s29, 5
	v_or_b32_e32 v150, v150, v131
	s_mul_i32 s38, s29, 0xc0
	s_ashr_i32 s29, s28, 31
	v_mov_b64_e32 v[138:139], s[50:51]
	s_ashr_i32 s39, s38, 31
	v_lshl_add_u64 v[158:159], v[150:151], 0, s[28:29]
	s_lshl_b64 s[30:31], s[38:39], 1
	v_mad_u64_u32 v[160:161], s[36:37], v158, s57, v[138:139]
	v_lshl_add_u64 v[162:163], v[156:157], 0, s[30:31]
	v_mad_i32_i24 v161, v159, s57, v161
	v_lshl_add_u64 v[158:159], v[162:163], 0, s[6:7]
	v_lshl_add_u64 v[160:161], v[160:161], 0, s[22:23]
	v_cndmask_b32_e32 v159, v161, v159, vcc
	v_cndmask_b32_e32 v158, v160, v158, vcc
	v_mov_b32_e32 v154, v124
	v_mov_b32_e32 v155, v127
	v_mov_b32_e32 v152, v125
	v_mov_b32_e32 v153, v126
	v_mov_b32_e32 v137, v129
	v_or_b32_e32 v135, 16, v136
	v_or_b32_e32 v144, v144, v135
	v_lshl_add_u64 v[158:159], v[158:159], 0, v[136:137]
	v_lshlrev_b32_e32 v144, 2, v144
	s_or_b32 s36, s28, 64
	s_addk_i32 s38, 0x180
	s_ashr_i32 s37, s36, 31
	s_ashr_i32 s39, s38, 31
	v_lshl_add_u64 v[150:151], v[150:151], 0, s[36:37]
	v_lshl_add_u64 v[156:157], s[38:39], 1, v[156:157]
	v_lshl_add_u64 v[156:157], v[156:157], 0, s[6:7]
	s_waitcnt vmcnt(0)
	v_pk_mul_f32 v[160:161], v[126:127], v[148:149]
	v_pk_mul_f32 v[162:163], v[124:125], v[146:147]
	v_mov_b32_e32 v164, v146
	v_mov_b32_e32 v165, v149
	v_mov_b32_e32 v146, v147
	v_mov_b32_e32 v147, v148
	v_mov_b32_e32 v148, v162
	v_mov_b32_e32 v149, v160
	v_mov_b32_e32 v160, v163
	v_pk_mul_f32 v[146:147], v[154:155], v[146:147]
	v_pk_add_f32 v[148:149], v[148:149], v[160:161] neg_lo:[0,1] neg_hi:[0,1]
	v_pk_fma_f32 v[146:147], v[152:153], v[164:165], v[146:147]
	v_pk_mul_f32 v[148:149], v[148:149], s[24:25] op_sel_hi:[1,0]
	v_pk_mul_f32 v[146:147], v[146:147], s[24:25] op_sel_hi:[1,0]
	v_cvt_pk_bf16_f32 v148, v148, v149
	v_cvt_pk_bf16_f32 v146, v146, v147
	v_mov_b32_e32 v216, v148
	v_mov_b32_e32 v217, v146
	global_load_dwordx4 v[146:149], v144, s[16:17]
	global_store_dword v[158:159], v216, off
	global_store_dword v[158:159], v217, off offset:64
	v_mov_b32_e32 v154, v120
	v_mov_b32_e32 v155, v123
	v_mov_b32_e32 v152, v121
	v_mov_b32_e32 v153, v122
	s_waitcnt vmcnt(2)
	v_pk_mul_f32 v[160:161], v[122:123], v[148:149]
	v_pk_mul_f32 v[162:163], v[120:121], v[146:147]
	v_mov_b32_e32 v164, v146
	v_mov_b32_e32 v165, v149
	v_mov_b32_e32 v146, v147
	v_mov_b32_e32 v147, v148
	v_mov_b32_e32 v148, v162
	v_mov_b32_e32 v149, v160
	v_mov_b32_e32 v160, v163
	v_pk_mul_f32 v[146:147], v[154:155], v[146:147]
	v_pk_add_f32 v[148:149], v[148:149], v[160:161] neg_lo:[0,1] neg_hi:[0,1]
	v_pk_fma_f32 v[146:147], v[152:153], v[164:165], v[146:147]
	v_pk_mul_f32 v[148:149], v[148:149], s[24:25] op_sel_hi:[1,0]
	v_pk_mul_f32 v[146:147], v[146:147], s[24:25] op_sel_hi:[1,0]
	v_cvt_pk_bf16_f32 v148, v148, v149
	v_cvt_pk_bf16_f32 v146, v146, v147
	v_mov_b32_e32 v216, v148
	v_mov_b32_e32 v217, v146
	global_load_dwordx4 v[146:149], v166, s[16:17]
	global_store_dword v[158:159], v216, off offset:16
	global_store_dword v[158:159], v217, off offset:80
	v_mad_u64_u32 v[158:159], s[38:39], v150, s57, v[138:139]
	v_mad_i32_i24 v159, v151, s57, v159
	v_lshl_add_u64 v[150:151], v[158:159], 0, s[22:23]
	v_cndmask_b32_e32 v151, v151, v157, vcc
	v_cndmask_b32_e32 v150, v150, v156, vcc
	v_lshl_add_u64 v[156:157], v[150:151], 0, v[136:137]
	v_mov_b32_e32 v154, v116
	v_mov_b32_e32 v155, v119
	v_mov_b32_e32 v152, v117
	v_mov_b32_e32 v153, v118
	s_waitcnt vmcnt(2)
	v_pk_mul_f32 v[150:151], v[118:119], v[148:149]
	v_pk_mul_f32 v[158:159], v[116:117], v[146:147]
	v_mov_b32_e32 v160, v146
	v_mov_b32_e32 v161, v149
	v_mov_b32_e32 v146, v147
	v_mov_b32_e32 v147, v148
	v_mov_b32_e32 v148, v158
	v_mov_b32_e32 v149, v150
	v_mov_b32_e32 v150, v159
	v_pk_mul_f32 v[146:147], v[154:155], v[146:147]
	v_pk_add_f32 v[148:149], v[148:149], v[150:151] neg_lo:[0,1] neg_hi:[0,1]
	v_pk_fma_f32 v[146:147], v[152:153], v[160:161], v[146:147]
	v_pk_mul_f32 v[148:149], v[148:149], s[24:25] op_sel_hi:[1,0]
	v_pk_mul_f32 v[146:147], v[146:147], s[24:25] op_sel_hi:[1,0]
	v_cvt_pk_bf16_f32 v148, v148, v149
	v_cvt_pk_bf16_f32 v146, v146, v147
	v_mov_b32_e32 v216, v148
	v_mov_b32_e32 v217, v146
	global_load_dwordx4 v[148:151], v144, s[16:17]
	global_store_dword v[156:157], v216, off
	global_store_dword v[156:157], v217, off offset:64
	v_add_u32_e32 v147, 16, v143
	v_or_b32_e32 v146, 0x1010, v131
	v_and_b32_e32 v144, 0xfdf, v147
	v_cmp_gt_i32_e32 vcc, s33, v147
	v_mov_b32_e32 v154, v112
	v_mov_b32_e32 v155, v115
	v_cndmask_b32_e32 v144, v146, v144, vcc
	v_mov_b32_e32 v152, v113
	v_mov_b32_e32 v153, v114
	v_lshlrev_b32_e32 v164, 6, v144
	v_or_b32_e32 v144, v164, v136
	v_lshlrev_b32_e32 v168, 2, v144
	s_waitcnt vmcnt(2)
	v_pk_mul_f32 v[158:159], v[114:115], v[150:151]
	v_pk_mul_f32 v[160:161], v[112:113], v[148:149]
	v_mov_b32_e32 v162, v148
	v_mov_b32_e32 v163, v151
	v_mov_b32_e32 v148, v149
	v_mov_b32_e32 v149, v150
	v_mov_b32_e32 v150, v160
	v_mov_b32_e32 v151, v158
	v_mov_b32_e32 v158, v161
	v_pk_mul_f32 v[148:149], v[154:155], v[148:149]
	v_pk_add_f32 v[150:151], v[150:151], v[158:159] neg_lo:[0,1] neg_hi:[0,1]
	v_pk_fma_f32 v[148:149], v[152:153], v[162:163], v[148:149]
	v_pk_mul_f32 v[150:151], v[150:151], s[24:25] op_sel_hi:[1,0]
	v_pk_mul_f32 v[148:149], v[148:149], s[24:25] op_sel_hi:[1,0]
	v_cvt_pk_bf16_f32 v144, v150, v151
	v_cvt_pk_bf16_f32 v148, v148, v149
	v_mov_b32_e32 v216, v144
	v_mov_b32_e32 v217, v148
	global_load_dwordx4 v[148:151], v168, s[16:17]
	global_store_dword v[156:157], v216, off offset:16
	global_store_dword v[156:157], v217, off offset:80
	v_lshrrev_b32_e32 v152, 5, v128
	v_mov_b32_e32 v153, v129
	v_or_b32_e32 v144, 16, v131
	v_lshlrev_b64 v[152:153], 8, v[152:153]
	v_or_b32_e32 v152, v152, v144
	v_lshl_add_u64 v[160:161], v[152:153], 0, s[28:29]
	v_mad_i64_i32 v[158:159], s[38:39], v147, s45, v[140:141]
	v_mad_u64_u32 v[162:163], s[38:39], v160, s57, v[138:139]
	v_lshl_add_u64 v[158:159], v[158:159], 0, s[30:31]
	v_mad_i32_i24 v163, v161, s57, v163
	v_lshl_add_u64 v[160:161], v[158:159], 0, s[6:7]
	v_lshl_add_u64 v[162:163], v[162:163], 0, s[22:23]
	v_or_b32_e32 v147, v164, v135
	v_cndmask_b32_e32 v161, v163, v161, vcc
	v_cndmask_b32_e32 v160, v162, v160, vcc
	v_mov_b32_e32 v156, v108
	v_mov_b32_e32 v157, v111
	v_mov_b32_e32 v154, v109
	v_mov_b32_e32 v155, v110
	v_lshl_add_u64 v[160:161], v[160:161], 0, v[136:137]
	v_lshlrev_b32_e32 v147, 2, v147
	v_lshl_add_u64 v[152:153], v[152:153], 0, s[36:37]
	v_lshl_add_u64 v[158:159], v[158:159], 0, s[26:27]
	s_waitcnt vmcnt(2)
	v_pk_mul_f32 v[162:163], v[110:111], v[150:151]
	v_pk_mul_f32 v[164:165], v[108:109], v[148:149]
	v_mov_b32_e32 v166, v148
	v_mov_b32_e32 v167, v151
	v_mov_b32_e32 v148, v149
	v_mov_b32_e32 v149, v150
	v_mov_b32_e32 v150, v164
	v_mov_b32_e32 v151, v162
	v_mov_b32_e32 v162, v165
	v_pk_mul_f32 v[148:149], v[156:157], v[148:149]
	v_pk_add_f32 v[150:151], v[150:151], v[162:163] neg_lo:[0,1] neg_hi:[0,1]
	v_pk_fma_f32 v[148:149], v[154:155], v[166:167], v[148:149]
	v_pk_mul_f32 v[150:151], v[150:151], s[24:25] op_sel_hi:[1,0]
	v_pk_mul_f32 v[148:149], v[148:149], s[24:25] op_sel_hi:[1,0]
	v_cvt_pk_bf16_f32 v150, v150, v151
	v_cvt_pk_bf16_f32 v148, v148, v149
	v_mov_b32_e32 v216, v150
	v_mov_b32_e32 v217, v148
	global_load_dwordx4 v[148:151], v147, s[16:17]
	global_store_dword v[160:161], v216, off
	global_store_dword v[160:161], v217, off offset:64
	v_mov_b32_e32 v156, v104
	v_mov_b32_e32 v157, v107
	v_mov_b32_e32 v154, v105
	v_mov_b32_e32 v155, v106
	s_waitcnt vmcnt(2)
	v_pk_mul_f32 v[162:163], v[106:107], v[150:151]
	v_pk_mul_f32 v[164:165], v[104:105], v[148:149]
	v_mov_b32_e32 v166, v148
	v_mov_b32_e32 v167, v151
	v_mov_b32_e32 v148, v149
	v_mov_b32_e32 v149, v150
	v_mov_b32_e32 v150, v164
	v_mov_b32_e32 v151, v162
	v_mov_b32_e32 v162, v165
	v_pk_mul_f32 v[148:149], v[156:157], v[148:149]
	v_pk_add_f32 v[150:151], v[150:151], v[162:163] neg_lo:[0,1] neg_hi:[0,1]
	v_pk_fma_f32 v[148:149], v[154:155], v[166:167], v[148:149]
	v_pk_mul_f32 v[150:151], v[150:151], s[24:25] op_sel_hi:[1,0]
	v_pk_mul_f32 v[148:149], v[148:149], s[24:25] op_sel_hi:[1,0]
	v_cvt_pk_bf16_f32 v150, v150, v151
	v_cvt_pk_bf16_f32 v148, v148, v149
	v_mov_b32_e32 v216, v150
	v_mov_b32_e32 v217, v148
	global_load_dwordx4 v[148:151], v168, s[16:17]
	global_store_dword v[160:161], v216, off offset:16
	global_store_dword v[160:161], v217, off offset:80
	v_mad_u64_u32 v[160:161], s[38:39], v152, s57, v[138:139]
	v_mad_i32_i24 v161, v153, s57, v161
	v_lshl_add_u64 v[152:153], v[160:161], 0, s[22:23]
	v_cndmask_b32_e32 v153, v153, v159, vcc
	v_cndmask_b32_e32 v152, v152, v158, vcc
	v_mov_b32_e32 v156, v100
	v_mov_b32_e32 v157, v103
	v_mov_b32_e32 v154, v101
	v_mov_b32_e32 v155, v102
	v_lshl_add_u64 v[152:153], v[152:153], 0, v[136:137]
	s_waitcnt vmcnt(2)
	v_pk_mul_f32 v[158:159], v[102:103], v[150:151]
	v_pk_mul_f32 v[160:161], v[100:101], v[148:149]
	v_mov_b32_e32 v162, v148
	v_mov_b32_e32 v163, v151
	v_mov_b32_e32 v148, v149
	v_mov_b32_e32 v149, v150
	v_mov_b32_e32 v150, v160
	v_mov_b32_e32 v151, v158
	v_mov_b32_e32 v158, v161
	v_pk_mul_f32 v[148:149], v[156:157], v[148:149]
	v_pk_add_f32 v[150:151], v[150:151], v[158:159] neg_lo:[0,1] neg_hi:[0,1]
	v_pk_fma_f32 v[148:149], v[154:155], v[162:163], v[148:149]
	v_pk_mul_f32 v[150:151], v[150:151], s[24:25] op_sel_hi:[1,0]
	v_pk_mul_f32 v[148:149], v[148:149], s[24:25] op_sel_hi:[1,0]
	v_cvt_pk_bf16_f32 v150, v150, v151
	v_cvt_pk_bf16_f32 v148, v148, v149
	v_mov_b32_e32 v216, v150
	v_mov_b32_e32 v217, v148
	global_load_dwordx4 v[148:151], v147, s[16:17]
	global_store_dword v[152:153], v216, off
	global_store_dword v[152:153], v217, off offset:64
	v_add_u32_e32 v147, 32, v143
	v_and_b32_e32 v158, 0xfef, v147
	v_cmp_gt_i32_e32 vcc, s33, v147
	v_mov_b32_e32 v156, v96
	v_mov_b32_e32 v157, v99
	v_cndmask_b32_e32 v158, v145, v158, vcc
	v_lshlrev_b32_e32 v164, 6, v158
	v_or_b32_e32 v158, v164, v136
	v_lshlrev_b32_e32 v168, 2, v158
	v_mov_b32_e32 v154, v97
	v_mov_b32_e32 v155, v98
	s_waitcnt vmcnt(2)
	v_pk_mul_f32 v[158:159], v[98:99], v[150:151]
	v_pk_mul_f32 v[160:161], v[96:97], v[148:149]
	v_mov_b32_e32 v162, v148
	v_mov_b32_e32 v163, v151
	v_mov_b32_e32 v148, v149
	v_mov_b32_e32 v149, v150
	v_mov_b32_e32 v150, v160
	v_mov_b32_e32 v151, v158
	v_mov_b32_e32 v158, v161
	v_pk_mul_f32 v[148:149], v[156:157], v[148:149]
	v_pk_add_f32 v[150:151], v[150:151], v[158:159] neg_lo:[0,1] neg_hi:[0,1]
	v_pk_fma_f32 v[148:149], v[154:155], v[162:163], v[148:149]
	v_pk_mul_f32 v[150:151], v[150:151], s[24:25] op_sel_hi:[1,0]
	v_pk_mul_f32 v[148:149], v[148:149], s[24:25] op_sel_hi:[1,0]
	v_cvt_pk_bf16_f32 v150, v150, v151
	v_cvt_pk_bf16_f32 v148, v148, v149
	v_mov_b32_e32 v216, v150
	v_mov_b32_e32 v217, v148
	global_load_dwordx4 v[148:151], v168, s[16:17]
	global_store_dword v[152:153], v216, off offset:16
	global_store_dword v[152:153], v217, off offset:80
	v_lshrrev_b32_e32 v152, 5, v132
	v_mov_b32_e32 v153, v129
	v_lshlrev_b64 v[152:153], 8, v[152:153]
	v_or_b32_e32 v152, v152, v131
	v_lshl_add_u64 v[160:161], v[152:153], 0, s[28:29]
	v_mad_i64_i32 v[158:159], s[38:39], v147, s45, v[140:141]
	v_mad_u64_u32 v[162:163], s[38:39], v160, s57, v[138:139]
	v_lshl_add_u64 v[158:159], v[158:159], 0, s[30:31]
	v_mad_i32_i24 v163, v161, s57, v163
	v_lshl_add_u64 v[160:161], v[158:159], 0, s[6:7]
	v_lshl_add_u64 v[162:163], v[162:163], 0, s[22:23]
	v_or_b32_e32 v147, v164, v135
	v_cndmask_b32_e32 v161, v163, v161, vcc
	v_cndmask_b32_e32 v160, v162, v160, vcc
	v_mov_b32_e32 v156, v92
	v_mov_b32_e32 v157, v95
	v_mov_b32_e32 v154, v93
	v_mov_b32_e32 v155, v94
	v_lshl_add_u64 v[160:161], v[160:161], 0, v[136:137]
	v_lshlrev_b32_e32 v147, 2, v147
	v_lshl_add_u64 v[152:153], v[152:153], 0, s[36:37]
	v_lshl_add_u64 v[158:159], v[158:159], 0, s[26:27]
	s_waitcnt vmcnt(2)
	v_pk_mul_f32 v[162:163], v[94:95], v[150:151]
	v_pk_mul_f32 v[164:165], v[92:93], v[148:149]
	v_mov_b32_e32 v166, v148
	v_mov_b32_e32 v167, v151
	v_mov_b32_e32 v148, v149
	v_mov_b32_e32 v149, v150
	v_mov_b32_e32 v150, v164
	v_mov_b32_e32 v151, v162
	v_mov_b32_e32 v162, v165
	v_pk_mul_f32 v[148:149], v[156:157], v[148:149]
	v_pk_add_f32 v[150:151], v[150:151], v[162:163] neg_lo:[0,1] neg_hi:[0,1]
	v_pk_fma_f32 v[148:149], v[154:155], v[166:167], v[148:149]
	v_pk_mul_f32 v[150:151], v[150:151], s[24:25] op_sel_hi:[1,0]
	v_pk_mul_f32 v[148:149], v[148:149], s[24:25] op_sel_hi:[1,0]
	v_cvt_pk_bf16_f32 v150, v150, v151
	v_cvt_pk_bf16_f32 v148, v148, v149
	v_mov_b32_e32 v216, v150
	v_mov_b32_e32 v217, v148
	global_load_dwordx4 v[148:151], v147, s[16:17]
	global_store_dword v[160:161], v216, off
	global_store_dword v[160:161], v217, off offset:64
	v_mov_b32_e32 v156, v88
	v_mov_b32_e32 v157, v91
	v_mov_b32_e32 v154, v89
	v_mov_b32_e32 v155, v90
	s_waitcnt vmcnt(2)
	v_pk_mul_f32 v[162:163], v[90:91], v[150:151]
	v_pk_mul_f32 v[164:165], v[88:89], v[148:149]
	v_mov_b32_e32 v166, v148
	v_mov_b32_e32 v167, v151
	v_mov_b32_e32 v148, v149
	v_mov_b32_e32 v149, v150
	v_mov_b32_e32 v150, v164
	v_mov_b32_e32 v151, v162
	v_mov_b32_e32 v162, v165
	v_pk_mul_f32 v[148:149], v[156:157], v[148:149]
	v_pk_add_f32 v[150:151], v[150:151], v[162:163] neg_lo:[0,1] neg_hi:[0,1]
	v_pk_fma_f32 v[148:149], v[154:155], v[166:167], v[148:149]
	v_pk_mul_f32 v[150:151], v[150:151], s[24:25] op_sel_hi:[1,0]
	v_pk_mul_f32 v[148:149], v[148:149], s[24:25] op_sel_hi:[1,0]
	v_cvt_pk_bf16_f32 v150, v150, v151
	v_cvt_pk_bf16_f32 v148, v148, v149
	v_mov_b32_e32 v216, v150
	v_mov_b32_e32 v217, v148
	global_load_dwordx4 v[148:151], v168, s[16:17]
	global_store_dword v[160:161], v216, off offset:16
	global_store_dword v[160:161], v217, off offset:80
	v_mad_u64_u32 v[160:161], s[38:39], v152, s57, v[138:139]
	v_mad_i32_i24 v161, v153, s57, v161
	v_lshl_add_u64 v[152:153], v[160:161], 0, s[22:23]
	v_cndmask_b32_e32 v153, v153, v159, vcc
	v_cndmask_b32_e32 v152, v152, v158, vcc
	v_mov_b32_e32 v156, v84
	v_mov_b32_e32 v157, v87
	v_mov_b32_e32 v154, v85
	v_mov_b32_e32 v155, v86
	v_lshl_add_u64 v[152:153], v[152:153], 0, v[136:137]
	s_waitcnt vmcnt(2)
	v_pk_mul_f32 v[158:159], v[86:87], v[150:151]
	v_pk_mul_f32 v[160:161], v[84:85], v[148:149]
	v_mov_b32_e32 v162, v148
	v_mov_b32_e32 v163, v151
	v_mov_b32_e32 v148, v149
	v_mov_b32_e32 v149, v150
	v_mov_b32_e32 v150, v160
	v_mov_b32_e32 v151, v158
	v_mov_b32_e32 v158, v161
	v_pk_mul_f32 v[148:149], v[156:157], v[148:149]
	v_pk_add_f32 v[150:151], v[150:151], v[158:159] neg_lo:[0,1] neg_hi:[0,1]
	v_pk_fma_f32 v[148:149], v[154:155], v[162:163], v[148:149]
	v_pk_mul_f32 v[150:151], v[150:151], s[24:25] op_sel_hi:[1,0]
	v_pk_mul_f32 v[148:149], v[148:149], s[24:25] op_sel_hi:[1,0]
	v_cvt_pk_bf16_f32 v150, v150, v151
	v_cvt_pk_bf16_f32 v148, v148, v149
	v_mov_b32_e32 v216, v150
	v_mov_b32_e32 v217, v148
	global_load_dwordx4 v[148:151], v147, s[16:17]
	global_store_dword v[152:153], v216, off
	global_store_dword v[152:153], v217, off offset:64
	v_add_u32_e32 v147, 48, v143
	v_and_b32_e32 v158, 0xfff, v147
	v_cmp_gt_i32_e32 vcc, s33, v147
	v_mov_b32_e32 v156, v80
	v_mov_b32_e32 v157, v83
	v_cndmask_b32_e32 v158, v146, v158, vcc
	v_lshlrev_b32_e32 v164, 6, v158
	v_or_b32_e32 v158, v164, v136
	v_lshlrev_b32_e32 v168, 2, v158
	v_mov_b32_e32 v154, v81
	v_mov_b32_e32 v155, v82
	s_waitcnt vmcnt(2)
	v_pk_mul_f32 v[158:159], v[82:83], v[150:151]
	v_pk_mul_f32 v[160:161], v[80:81], v[148:149]
	v_mov_b32_e32 v162, v148
	v_mov_b32_e32 v163, v151
	v_mov_b32_e32 v148, v149
	v_mov_b32_e32 v149, v150
	v_mov_b32_e32 v150, v160
	v_mov_b32_e32 v151, v158
	v_mov_b32_e32 v158, v161
	v_pk_mul_f32 v[148:149], v[156:157], v[148:149]
	v_pk_add_f32 v[150:151], v[150:151], v[158:159] neg_lo:[0,1] neg_hi:[0,1]
	v_pk_fma_f32 v[148:149], v[154:155], v[162:163], v[148:149]
	v_pk_mul_f32 v[150:151], v[150:151], s[24:25] op_sel_hi:[1,0]
	v_pk_mul_f32 v[148:149], v[148:149], s[24:25] op_sel_hi:[1,0]
	v_cvt_pk_bf16_f32 v150, v150, v151
	v_cvt_pk_bf16_f32 v148, v148, v149
	v_mov_b32_e32 v216, v150
	v_mov_b32_e32 v217, v148
	global_load_dwordx4 v[148:151], v168, s[16:17]
	global_store_dword v[152:153], v216, off offset:16
	global_store_dword v[152:153], v217, off offset:80
	v_lshrrev_b32_e32 v152, 5, v130
	v_mov_b32_e32 v153, v129
	v_lshlrev_b64 v[152:153], 8, v[152:153]
	v_or_b32_e32 v152, v152, v144
	v_lshl_add_u64 v[160:161], v[152:153], 0, s[28:29]
	v_mad_i64_i32 v[158:159], s[38:39], v147, s45, v[140:141]
	v_mad_u64_u32 v[162:163], s[38:39], v160, s57, v[138:139]
	v_lshl_add_u64 v[158:159], v[158:159], 0, s[30:31]
	v_mad_i32_i24 v163, v161, s57, v163
	v_lshl_add_u64 v[160:161], v[158:159], 0, s[6:7]
	v_lshl_add_u64 v[162:163], v[162:163], 0, s[22:23]
	v_or_b32_e32 v147, v164, v135
	v_cndmask_b32_e32 v161, v163, v161, vcc
	v_cndmask_b32_e32 v160, v162, v160, vcc
	v_mov_b32_e32 v156, v76
	v_mov_b32_e32 v157, v79
	v_mov_b32_e32 v154, v77
	v_mov_b32_e32 v155, v78
	v_lshl_add_u64 v[160:161], v[160:161], 0, v[136:137]
	v_lshlrev_b32_e32 v147, 2, v147
	v_lshl_add_u64 v[152:153], v[152:153], 0, s[36:37]
	v_lshl_add_u64 v[158:159], v[158:159], 0, s[26:27]
	s_waitcnt vmcnt(2)
	v_pk_mul_f32 v[162:163], v[78:79], v[150:151]
	v_pk_mul_f32 v[164:165], v[76:77], v[148:149]
	v_mov_b32_e32 v166, v148
	v_mov_b32_e32 v167, v151
	v_mov_b32_e32 v148, v149
	v_mov_b32_e32 v149, v150
	v_mov_b32_e32 v150, v164
	v_mov_b32_e32 v151, v162
	v_mov_b32_e32 v162, v165
	v_pk_mul_f32 v[148:149], v[156:157], v[148:149]
	v_pk_add_f32 v[150:151], v[150:151], v[162:163] neg_lo:[0,1] neg_hi:[0,1]
	v_pk_fma_f32 v[148:149], v[154:155], v[166:167], v[148:149]
	v_pk_mul_f32 v[150:151], v[150:151], s[24:25] op_sel_hi:[1,0]
	v_pk_mul_f32 v[148:149], v[148:149], s[24:25] op_sel_hi:[1,0]
	v_cvt_pk_bf16_f32 v150, v150, v151
	v_cvt_pk_bf16_f32 v148, v148, v149
	v_mov_b32_e32 v216, v150
	v_mov_b32_e32 v217, v148
	global_load_dwordx4 v[148:151], v147, s[16:17]
	global_store_dword v[160:161], v216, off
	global_store_dword v[160:161], v217, off offset:64
	v_mov_b32_e32 v156, v72
	v_mov_b32_e32 v157, v75
	v_mov_b32_e32 v154, v73
	v_mov_b32_e32 v155, v74
	s_waitcnt vmcnt(2)
	v_pk_mul_f32 v[162:163], v[74:75], v[150:151]
	v_pk_mul_f32 v[164:165], v[72:73], v[148:149]
	v_mov_b32_e32 v166, v148
	v_mov_b32_e32 v167, v151
	v_mov_b32_e32 v148, v149
	v_mov_b32_e32 v149, v150
	v_mov_b32_e32 v150, v164
	v_mov_b32_e32 v151, v162
	v_mov_b32_e32 v162, v165
	v_pk_mul_f32 v[148:149], v[156:157], v[148:149]
	v_pk_add_f32 v[150:151], v[150:151], v[162:163] neg_lo:[0,1] neg_hi:[0,1]
	v_pk_fma_f32 v[148:149], v[154:155], v[166:167], v[148:149]
	v_pk_mul_f32 v[150:151], v[150:151], s[24:25] op_sel_hi:[1,0]
	v_pk_mul_f32 v[148:149], v[148:149], s[24:25] op_sel_hi:[1,0]
	v_cvt_pk_bf16_f32 v150, v150, v151
	v_cvt_pk_bf16_f32 v148, v148, v149
	v_mov_b32_e32 v216, v150
	v_mov_b32_e32 v217, v148
	global_load_dwordx4 v[148:151], v168, s[16:17]
	global_store_dword v[160:161], v216, off offset:16
	global_store_dword v[160:161], v217, off offset:80
	v_mad_u64_u32 v[160:161], s[38:39], v152, s57, v[138:139]
	v_mad_i32_i24 v161, v153, s57, v161
	v_lshl_add_u64 v[152:153], v[160:161], 0, s[22:23]
	v_cndmask_b32_e32 v153, v153, v159, vcc
	v_cndmask_b32_e32 v152, v152, v158, vcc
	v_mov_b32_e32 v156, v68
	v_mov_b32_e32 v157, v71
	v_mov_b32_e32 v154, v69
	v_mov_b32_e32 v155, v70
	v_lshl_add_u64 v[152:153], v[152:153], 0, v[136:137]
	s_waitcnt vmcnt(2)
	v_pk_mul_f32 v[158:159], v[70:71], v[150:151]
	v_pk_mul_f32 v[160:161], v[68:69], v[148:149]
	v_mov_b32_e32 v162, v148
	v_mov_b32_e32 v163, v151
	v_mov_b32_e32 v148, v149
	v_mov_b32_e32 v149, v150
	v_mov_b32_e32 v150, v160
	v_mov_b32_e32 v151, v158
	v_mov_b32_e32 v158, v161
	v_pk_mul_f32 v[148:149], v[156:157], v[148:149]
	v_pk_add_f32 v[150:151], v[150:151], v[158:159] neg_lo:[0,1] neg_hi:[0,1]
	v_pk_fma_f32 v[148:149], v[154:155], v[162:163], v[148:149]
	v_pk_mul_f32 v[150:151], v[150:151], s[24:25] op_sel_hi:[1,0]
	v_pk_mul_f32 v[148:149], v[148:149], s[24:25] op_sel_hi:[1,0]
	v_cvt_pk_bf16_f32 v150, v150, v151
	v_cvt_pk_bf16_f32 v148, v148, v149
	v_mov_b32_e32 v216, v150
	v_mov_b32_e32 v217, v148
	global_load_dwordx4 v[148:151], v147, s[16:17]
	global_store_dword v[152:153], v216, off
	global_store_dword v[152:153], v217, off offset:64
	v_add_u32_e32 v147, 0x80, v143
	v_and_b32_e32 v158, 0xfcf, v147
	v_cmp_gt_i32_e32 vcc, s33, v147
	v_mov_b32_e32 v156, v64
	v_mov_b32_e32 v157, v67
	v_cndmask_b32_e32 v158, v145, v158, vcc
	v_lshlrev_b32_e32 v164, 6, v158
	v_or_b32_e32 v158, v164, v136
	v_lshlrev_b32_e32 v168, 2, v158
	v_mov_b32_e32 v154, v65
	v_mov_b32_e32 v155, v66
	s_waitcnt vmcnt(2)
	v_pk_mul_f32 v[158:159], v[66:67], v[150:151]
	v_pk_mul_f32 v[160:161], v[64:65], v[148:149]
	v_mov_b32_e32 v162, v148
	v_mov_b32_e32 v163, v151
	v_mov_b32_e32 v148, v149
	v_mov_b32_e32 v149, v150
	v_mov_b32_e32 v150, v160
	v_mov_b32_e32 v151, v158
	v_mov_b32_e32 v158, v161
	v_pk_mul_f32 v[148:149], v[156:157], v[148:149]
	v_pk_add_f32 v[150:151], v[150:151], v[158:159] neg_lo:[0,1] neg_hi:[0,1]
	v_pk_fma_f32 v[148:149], v[154:155], v[162:163], v[148:149]
	v_pk_mul_f32 v[150:151], v[150:151], s[24:25] op_sel_hi:[1,0]
	v_pk_mul_f32 v[148:149], v[148:149], s[24:25] op_sel_hi:[1,0]
	v_cvt_pk_bf16_f32 v150, v150, v151
	v_cvt_pk_bf16_f32 v148, v148, v149
	v_mov_b32_e32 v216, v150
	v_mov_b32_e32 v217, v148
	global_load_dwordx4 v[148:151], v168, s[16:17]
	global_store_dword v[152:153], v216, off offset:16
	global_store_dword v[152:153], v217, off offset:80
	v_add_u32_e32 v152, 0xffffe080, v143
	v_mov_b32_e32 v153, v129
	v_lshrrev_b32_e32 v152, 5, v152
	v_lshlrev_b64 v[152:153], 8, v[152:153]
	v_or_b32_e32 v152, v152, v131
	v_lshl_add_u64 v[160:161], v[152:153], 0, s[28:29]
	v_mad_i64_i32 v[158:159], s[38:39], v147, s45, v[140:141]
	v_mad_u64_u32 v[162:163], s[38:39], v160, s57, v[138:139]
	v_lshl_add_u64 v[158:159], v[158:159], 0, s[30:31]
	v_mad_i32_i24 v163, v161, s57, v163
	v_lshl_add_u64 v[160:161], v[158:159], 0, s[6:7]
	v_lshl_add_u64 v[162:163], v[162:163], 0, s[22:23]
	v_or_b32_e32 v147, v164, v135
	v_cndmask_b32_e32 v161, v163, v161, vcc
	v_cndmask_b32_e32 v160, v162, v160, vcc
	v_mov_b32_e32 v156, v60
	v_mov_b32_e32 v157, v63
	v_mov_b32_e32 v154, v61
	v_mov_b32_e32 v155, v62
	v_lshl_add_u64 v[160:161], v[160:161], 0, v[136:137]
	v_lshlrev_b32_e32 v147, 2, v147
	v_lshl_add_u64 v[152:153], v[152:153], 0, s[36:37]
	v_lshl_add_u64 v[158:159], v[158:159], 0, s[26:27]
	s_waitcnt vmcnt(2)
	v_pk_mul_f32 v[162:163], v[62:63], v[150:151]
	v_pk_mul_f32 v[164:165], v[60:61], v[148:149]
	v_mov_b32_e32 v166, v148
	v_mov_b32_e32 v167, v151
	v_mov_b32_e32 v148, v149
	v_mov_b32_e32 v149, v150
	v_mov_b32_e32 v150, v164
	v_mov_b32_e32 v151, v162
	v_mov_b32_e32 v162, v165
	v_pk_mul_f32 v[148:149], v[156:157], v[148:149]
	v_pk_add_f32 v[150:151], v[150:151], v[162:163] neg_lo:[0,1] neg_hi:[0,1]
	v_pk_fma_f32 v[148:149], v[154:155], v[166:167], v[148:149]
	v_pk_mul_f32 v[150:151], v[150:151], s[24:25] op_sel_hi:[1,0]
	v_pk_mul_f32 v[148:149], v[148:149], s[24:25] op_sel_hi:[1,0]
	v_cvt_pk_bf16_f32 v150, v150, v151
	v_cvt_pk_bf16_f32 v148, v148, v149
	v_mov_b32_e32 v216, v150
	v_mov_b32_e32 v217, v148
	global_load_dwordx4 v[148:151], v147, s[16:17]
	global_store_dword v[160:161], v216, off
	global_store_dword v[160:161], v217, off offset:64
	v_mov_b32_e32 v156, v56
	v_mov_b32_e32 v157, v59
	v_mov_b32_e32 v154, v57
	v_mov_b32_e32 v155, v58
	s_waitcnt vmcnt(2)
	v_pk_mul_f32 v[162:163], v[58:59], v[150:151]
	v_pk_mul_f32 v[164:165], v[56:57], v[148:149]
	v_mov_b32_e32 v166, v148
	v_mov_b32_e32 v167, v151
	v_mov_b32_e32 v148, v149
	v_mov_b32_e32 v149, v150
	v_mov_b32_e32 v150, v164
	v_mov_b32_e32 v151, v162
	v_mov_b32_e32 v162, v165
	v_pk_mul_f32 v[148:149], v[156:157], v[148:149]
	v_pk_add_f32 v[150:151], v[150:151], v[162:163] neg_lo:[0,1] neg_hi:[0,1]
	v_pk_fma_f32 v[148:149], v[154:155], v[166:167], v[148:149]
	v_pk_mul_f32 v[150:151], v[150:151], s[24:25] op_sel_hi:[1,0]
	v_pk_mul_f32 v[148:149], v[148:149], s[24:25] op_sel_hi:[1,0]
	v_cvt_pk_bf16_f32 v150, v150, v151
	v_cvt_pk_bf16_f32 v148, v148, v149
	v_mov_b32_e32 v216, v150
	v_mov_b32_e32 v217, v148
	global_load_dwordx4 v[148:151], v168, s[16:17]
	global_store_dword v[160:161], v216, off offset:16
	global_store_dword v[160:161], v217, off offset:80
	v_mad_u64_u32 v[160:161], s[38:39], v152, s57, v[138:139]
	v_mad_i32_i24 v161, v153, s57, v161
	v_lshl_add_u64 v[152:153], v[160:161], 0, s[22:23]
	v_cndmask_b32_e32 v153, v153, v159, vcc
	v_cndmask_b32_e32 v152, v152, v158, vcc
	v_mov_b32_e32 v156, v52
	v_mov_b32_e32 v157, v55
	v_mov_b32_e32 v154, v53
	v_mov_b32_e32 v155, v54
	v_lshl_add_u64 v[152:153], v[152:153], 0, v[136:137]
	s_waitcnt vmcnt(2)
	v_pk_mul_f32 v[158:159], v[54:55], v[150:151]
	v_pk_mul_f32 v[160:161], v[52:53], v[148:149]
	v_mov_b32_e32 v162, v148
	v_mov_b32_e32 v163, v151
	v_mov_b32_e32 v148, v149
	v_mov_b32_e32 v149, v150
	v_mov_b32_e32 v150, v160
	v_mov_b32_e32 v151, v158
	v_mov_b32_e32 v158, v161
	v_pk_mul_f32 v[148:149], v[156:157], v[148:149]
	v_pk_add_f32 v[150:151], v[150:151], v[158:159] neg_lo:[0,1] neg_hi:[0,1]
	v_pk_fma_f32 v[148:149], v[154:155], v[162:163], v[148:149]
	v_pk_mul_f32 v[150:151], v[150:151], s[24:25] op_sel_hi:[1,0]
	v_pk_mul_f32 v[148:149], v[148:149], s[24:25] op_sel_hi:[1,0]
	v_cvt_pk_bf16_f32 v150, v150, v151
	v_cvt_pk_bf16_f32 v148, v148, v149
	v_mov_b32_e32 v216, v150
	v_mov_b32_e32 v217, v148
	global_load_dwordx4 v[148:151], v147, s[16:17]
	global_store_dword v[152:153], v216, off
	global_store_dword v[152:153], v217, off offset:64
	v_add_u32_e32 v147, 0x90, v143
	v_and_b32_e32 v158, 0xfdf, v147
	v_cmp_gt_i32_e32 vcc, s33, v147
	v_mov_b32_e32 v156, v48
	v_mov_b32_e32 v157, v51
	v_cndmask_b32_e32 v158, v146, v158, vcc
	v_lshlrev_b32_e32 v164, 6, v158
	v_or_b32_e32 v158, v164, v136
	v_lshlrev_b32_e32 v168, 2, v158
	v_mov_b32_e32 v154, v49
	v_mov_b32_e32 v155, v50
	s_waitcnt vmcnt(2)
	v_pk_mul_f32 v[158:159], v[50:51], v[150:151]
	v_pk_mul_f32 v[160:161], v[48:49], v[148:149]
	v_mov_b32_e32 v162, v148
	v_mov_b32_e32 v163, v151
	v_mov_b32_e32 v148, v149
	v_mov_b32_e32 v149, v150
	v_mov_b32_e32 v150, v160
	v_mov_b32_e32 v151, v158
	v_mov_b32_e32 v158, v161
	v_pk_mul_f32 v[148:149], v[156:157], v[148:149]
	v_pk_add_f32 v[150:151], v[150:151], v[158:159] neg_lo:[0,1] neg_hi:[0,1]
	v_pk_fma_f32 v[148:149], v[154:155], v[162:163], v[148:149]
	v_pk_mul_f32 v[150:151], v[150:151], s[24:25] op_sel_hi:[1,0]
	v_pk_mul_f32 v[148:149], v[148:149], s[24:25] op_sel_hi:[1,0]
	v_cvt_pk_bf16_f32 v150, v150, v151
	v_cvt_pk_bf16_f32 v148, v148, v149
	v_mov_b32_e32 v216, v150
	v_mov_b32_e32 v217, v148
	global_load_dwordx4 v[148:151], v168, s[16:17]
	global_store_dword v[152:153], v216, off offset:16
	global_store_dword v[152:153], v217, off offset:80
	v_add_u32_e32 v152, 0xffffe090, v143
	v_mov_b32_e32 v153, v129
	v_lshrrev_b32_e32 v152, 5, v152
	v_lshlrev_b64 v[152:153], 8, v[152:153]
	v_or_b32_e32 v152, v152, v144
	v_lshl_add_u64 v[160:161], v[152:153], 0, s[28:29]
	v_mad_i64_i32 v[158:159], s[38:39], v147, s45, v[140:141]
	v_mad_u64_u32 v[162:163], s[38:39], v160, s57, v[138:139]
	v_lshl_add_u64 v[158:159], v[158:159], 0, s[30:31]
	v_mad_i32_i24 v163, v161, s57, v163
	v_lshl_add_u64 v[160:161], v[158:159], 0, s[6:7]
	v_lshl_add_u64 v[162:163], v[162:163], 0, s[22:23]
	v_or_b32_e32 v147, v164, v135
	v_cndmask_b32_e32 v161, v163, v161, vcc
	v_cndmask_b32_e32 v160, v162, v160, vcc
	v_mov_b32_e32 v156, v44
	v_mov_b32_e32 v157, v47
	v_mov_b32_e32 v154, v45
	v_mov_b32_e32 v155, v46
	v_lshl_add_u64 v[160:161], v[160:161], 0, v[136:137]
	v_lshlrev_b32_e32 v147, 2, v147
	v_lshl_add_u64 v[152:153], v[152:153], 0, s[36:37]
	v_lshl_add_u64 v[158:159], v[158:159], 0, s[26:27]
	s_waitcnt vmcnt(2)
	v_pk_mul_f32 v[162:163], v[46:47], v[150:151]
	v_pk_mul_f32 v[164:165], v[44:45], v[148:149]
	v_mov_b32_e32 v166, v148
	v_mov_b32_e32 v167, v151
	v_mov_b32_e32 v148, v149
	v_mov_b32_e32 v149, v150
	v_mov_b32_e32 v150, v164
	v_mov_b32_e32 v151, v162
	v_mov_b32_e32 v162, v165
	v_pk_mul_f32 v[148:149], v[156:157], v[148:149]
	v_pk_add_f32 v[150:151], v[150:151], v[162:163] neg_lo:[0,1] neg_hi:[0,1]
	v_pk_fma_f32 v[148:149], v[154:155], v[166:167], v[148:149]
	v_pk_mul_f32 v[150:151], v[150:151], s[24:25] op_sel_hi:[1,0]
	v_pk_mul_f32 v[148:149], v[148:149], s[24:25] op_sel_hi:[1,0]
	v_cvt_pk_bf16_f32 v150, v150, v151
	v_cvt_pk_bf16_f32 v148, v148, v149
	v_mov_b32_e32 v216, v150
	v_mov_b32_e32 v217, v148
	global_load_dwordx4 v[148:151], v147, s[16:17]
	global_store_dword v[160:161], v216, off
	global_store_dword v[160:161], v217, off offset:64
	v_mov_b32_e32 v156, v40
	v_mov_b32_e32 v157, v43
	v_mov_b32_e32 v154, v41
	v_mov_b32_e32 v155, v42
	s_waitcnt vmcnt(2)
	v_pk_mul_f32 v[162:163], v[42:43], v[150:151]
	v_pk_mul_f32 v[164:165], v[40:41], v[148:149]
	v_mov_b32_e32 v166, v148
	v_mov_b32_e32 v167, v151
	v_mov_b32_e32 v148, v149
	v_mov_b32_e32 v149, v150
	v_mov_b32_e32 v150, v164
	v_mov_b32_e32 v151, v162
	v_mov_b32_e32 v162, v165
	v_pk_mul_f32 v[148:149], v[156:157], v[148:149]
	v_pk_add_f32 v[150:151], v[150:151], v[162:163] neg_lo:[0,1] neg_hi:[0,1]
	v_pk_fma_f32 v[148:149], v[154:155], v[166:167], v[148:149]
	v_pk_mul_f32 v[150:151], v[150:151], s[24:25] op_sel_hi:[1,0]
	v_pk_mul_f32 v[148:149], v[148:149], s[24:25] op_sel_hi:[1,0]
	v_cvt_pk_bf16_f32 v150, v150, v151
	v_cvt_pk_bf16_f32 v148, v148, v149
	v_mov_b32_e32 v216, v150
	v_mov_b32_e32 v217, v148
	global_load_dwordx4 v[148:151], v168, s[16:17]
	global_store_dword v[160:161], v216, off offset:16
	global_store_dword v[160:161], v217, off offset:80
	v_mad_u64_u32 v[160:161], s[38:39], v152, s57, v[138:139]
	v_mad_i32_i24 v161, v153, s57, v161
	v_lshl_add_u64 v[152:153], v[160:161], 0, s[22:23]
	v_cndmask_b32_e32 v153, v153, v159, vcc
	v_cndmask_b32_e32 v152, v152, v158, vcc
	v_mov_b32_e32 v156, v36
	v_mov_b32_e32 v157, v39
	v_mov_b32_e32 v154, v37
	v_mov_b32_e32 v155, v38
	v_lshl_add_u64 v[152:153], v[152:153], 0, v[136:137]
	s_waitcnt vmcnt(2)
	v_pk_mul_f32 v[158:159], v[38:39], v[150:151]
	v_pk_mul_f32 v[160:161], v[36:37], v[148:149]
	v_mov_b32_e32 v162, v148
	v_mov_b32_e32 v163, v151
	v_mov_b32_e32 v148, v149
	v_mov_b32_e32 v149, v150
	v_mov_b32_e32 v150, v160
	v_mov_b32_e32 v151, v158
	v_mov_b32_e32 v158, v161
	v_pk_mul_f32 v[148:149], v[156:157], v[148:149]
	v_pk_add_f32 v[150:151], v[150:151], v[158:159] neg_lo:[0,1] neg_hi:[0,1]
	v_pk_fma_f32 v[148:149], v[154:155], v[162:163], v[148:149]
	v_pk_mul_f32 v[150:151], v[150:151], s[24:25] op_sel_hi:[1,0]
	v_pk_mul_f32 v[148:149], v[148:149], s[24:25] op_sel_hi:[1,0]
	v_cvt_pk_bf16_f32 v150, v150, v151
	v_cvt_pk_bf16_f32 v148, v148, v149
	v_mov_b32_e32 v216, v150
	v_mov_b32_e32 v217, v148
	global_load_dwordx4 v[148:151], v147, s[16:17]
	global_store_dword v[152:153], v216, off
	global_store_dword v[152:153], v217, off offset:64
	v_add_u32_e32 v147, 0xa0, v143
	v_and_b32_e32 v158, 0xfef, v147
	v_cmp_gt_i32_e32 vcc, s33, v147
	v_mov_b32_e32 v156, v32
	v_mov_b32_e32 v157, v35
	v_cndmask_b32_e32 v145, v145, v158, vcc
	v_lshlrev_b32_e32 v145, 6, v145
	v_or_b32_e32 v158, v145, v136
	v_lshlrev_b32_e32 v168, 2, v158
	v_mov_b32_e32 v154, v33
	v_mov_b32_e32 v155, v34
	s_waitcnt vmcnt(2)
	v_pk_mul_f32 v[158:159], v[34:35], v[150:151]
	v_pk_mul_f32 v[160:161], v[32:33], v[148:149]
	v_mov_b32_e32 v162, v148
	v_mov_b32_e32 v163, v151
	v_mov_b32_e32 v148, v149
	v_mov_b32_e32 v149, v150
	v_mov_b32_e32 v150, v160
	v_mov_b32_e32 v151, v158
	v_mov_b32_e32 v158, v161
	v_pk_mul_f32 v[148:149], v[156:157], v[148:149]
	v_pk_add_f32 v[150:151], v[150:151], v[158:159] neg_lo:[0,1] neg_hi:[0,1]
	v_pk_fma_f32 v[148:149], v[154:155], v[162:163], v[148:149]
	v_pk_mul_f32 v[150:151], v[150:151], s[24:25] op_sel_hi:[1,0]
	v_pk_mul_f32 v[148:149], v[148:149], s[24:25] op_sel_hi:[1,0]
	v_cvt_pk_bf16_f32 v150, v150, v151
	v_cvt_pk_bf16_f32 v148, v148, v149
	v_mov_b32_e32 v216, v150
	v_mov_b32_e32 v217, v148
	global_load_dwordx4 v[148:151], v168, s[16:17]
	global_store_dword v[152:153], v216, off offset:16
	global_store_dword v[152:153], v217, off offset:80
	v_add_u32_e32 v152, 0xffffe0a0, v143
	v_mov_b32_e32 v153, v129
	v_lshrrev_b32_e32 v152, 5, v152
	v_lshlrev_b64 v[152:153], 8, v[152:153]
	v_or_b32_e32 v152, v152, v131
	v_lshl_add_u64 v[160:161], v[152:153], 0, s[28:29]
	v_mad_i64_i32 v[158:159], s[38:39], v147, s45, v[140:141]
	v_mad_u64_u32 v[162:163], s[38:39], v160, s57, v[138:139]
	v_lshl_add_u64 v[158:159], v[158:159], 0, s[30:31]
	v_mad_i32_i24 v163, v161, s57, v163
	v_lshl_add_u64 v[160:161], v[158:159], 0, s[6:7]
	v_lshl_add_u64 v[162:163], v[162:163], 0, s[22:23]
	v_cndmask_b32_e32 v161, v163, v161, vcc
	v_cndmask_b32_e32 v160, v162, v160, vcc
	v_mov_b32_e32 v156, v28
	v_mov_b32_e32 v157, v31
	v_mov_b32_e32 v154, v29
	v_mov_b32_e32 v155, v30
	v_or_b32_e32 v131, v145, v135
	v_lshl_add_u64 v[160:161], v[160:161], 0, v[136:137]
	v_lshlrev_b32_e32 v131, 2, v131
	v_lshl_add_u64 v[152:153], v[152:153], 0, s[36:37]
	v_lshl_add_u64 v[158:159], v[158:159], 0, s[26:27]
	s_waitcnt vmcnt(2)
	v_pk_mul_f32 v[162:163], v[30:31], v[150:151]
	v_pk_mul_f32 v[164:165], v[28:29], v[148:149]
	v_mov_b32_e32 v166, v148
	v_mov_b32_e32 v167, v151
	v_mov_b32_e32 v148, v149
	v_mov_b32_e32 v149, v150
	v_mov_b32_e32 v150, v164
	v_mov_b32_e32 v151, v162
	v_mov_b32_e32 v162, v165
	v_pk_mul_f32 v[148:149], v[156:157], v[148:149]
	v_pk_add_f32 v[150:151], v[150:151], v[162:163] neg_lo:[0,1] neg_hi:[0,1]
	v_pk_fma_f32 v[148:149], v[154:155], v[166:167], v[148:149]
	v_pk_mul_f32 v[150:151], v[150:151], s[24:25] op_sel_hi:[1,0]
	v_pk_mul_f32 v[148:149], v[148:149], s[24:25] op_sel_hi:[1,0]
	v_cvt_pk_bf16_f32 v145, v150, v151
	v_cvt_pk_bf16_f32 v147, v148, v149
	v_mov_b32_e32 v216, v145
	v_mov_b32_e32 v217, v147
	global_load_dwordx4 v[148:151], v131, s[16:17]
	global_store_dword v[160:161], v216, off
	global_store_dword v[160:161], v217, off offset:64
	v_mov_b32_e32 v156, v24
	v_mov_b32_e32 v157, v27
	v_mov_b32_e32 v154, v25
	v_mov_b32_e32 v155, v26
	s_waitcnt vmcnt(2)
	v_pk_mul_f32 v[162:163], v[26:27], v[150:151]
	v_pk_mul_f32 v[164:165], v[24:25], v[148:149]
	v_mov_b32_e32 v166, v148
	v_mov_b32_e32 v167, v151
	v_mov_b32_e32 v148, v149
	v_mov_b32_e32 v149, v150
	v_mov_b32_e32 v150, v164
	v_mov_b32_e32 v151, v162
	v_mov_b32_e32 v162, v165
	v_pk_mul_f32 v[148:149], v[156:157], v[148:149]
	v_pk_add_f32 v[150:151], v[150:151], v[162:163] neg_lo:[0,1] neg_hi:[0,1]
	v_pk_fma_f32 v[148:149], v[154:155], v[166:167], v[148:149]
	v_pk_mul_f32 v[150:151], v[150:151], s[24:25] op_sel_hi:[1,0]
	v_pk_mul_f32 v[148:149], v[148:149], s[24:25] op_sel_hi:[1,0]
	v_cvt_pk_bf16_f32 v145, v150, v151
	v_cvt_pk_bf16_f32 v147, v148, v149
	v_mov_b32_e32 v216, v145
	v_mov_b32_e32 v217, v147
	global_load_dwordx4 v[148:151], v168, s[16:17]
	global_store_dword v[160:161], v216, off offset:16
	global_store_dword v[160:161], v217, off offset:80
	v_mad_u64_u32 v[160:161], s[38:39], v152, s57, v[138:139]
	v_mad_i32_i24 v161, v153, s57, v161
	v_lshl_add_u64 v[152:153], v[160:161], 0, s[22:23]
	v_cndmask_b32_e32 v153, v153, v159, vcc
	v_cndmask_b32_e32 v152, v152, v158, vcc
	v_mov_b32_e32 v156, v20
	v_mov_b32_e32 v157, v23
	v_mov_b32_e32 v154, v21
	v_mov_b32_e32 v155, v22
	v_lshl_add_u64 v[152:153], v[152:153], 0, v[136:137]
	s_waitcnt vmcnt(2)
	v_pk_mul_f32 v[158:159], v[22:23], v[150:151]
	v_pk_mul_f32 v[160:161], v[20:21], v[148:149]
	v_mov_b32_e32 v162, v148
	v_mov_b32_e32 v163, v151
	v_mov_b32_e32 v148, v149
	v_mov_b32_e32 v149, v150
	v_mov_b32_e32 v150, v160
	v_mov_b32_e32 v151, v158
	v_mov_b32_e32 v158, v161
	v_pk_mul_f32 v[148:149], v[156:157], v[148:149]
	v_pk_add_f32 v[150:151], v[150:151], v[158:159] neg_lo:[0,1] neg_hi:[0,1]
	v_pk_fma_f32 v[148:149], v[154:155], v[162:163], v[148:149]
	v_pk_mul_f32 v[150:151], v[150:151], s[24:25] op_sel_hi:[1,0]
	v_pk_mul_f32 v[148:149], v[148:149], s[24:25] op_sel_hi:[1,0]
	v_cvt_pk_bf16_f32 v145, v150, v151
	v_cvt_pk_bf16_f32 v147, v148, v149
	v_mov_b32_e32 v216, v145
	v_mov_b32_e32 v217, v147
	global_load_dwordx4 v[148:151], v131, s[16:17]
	global_store_dword v[152:153], v216, off
	global_store_dword v[152:153], v217, off offset:64
	v_add_u32_e32 v131, 0xb0, v143
	v_and_b32_e32 v145, 0xfff, v131
	v_cmp_gt_i32_e32 vcc, s33, v131
	v_mov_b32_e32 v156, v16
	v_mov_b32_e32 v157, v19
	v_cndmask_b32_e32 v145, v146, v145, vcc
	v_lshlrev_b32_e32 v145, 6, v145
	v_or_b32_e32 v146, v145, v136
	v_lshlrev_b32_e32 v162, 2, v146
	v_mov_b32_e32 v154, v17
	v_mov_b32_e32 v155, v18
	v_mad_i64_i32 v[140:141], s[38:39], v131, s45, v[140:141]
	v_or_b32_e32 v131, v145, v135
	v_lshl_add_u64 v[140:141], v[140:141], 0, s[30:31]
	v_lshlrev_b32_e32 v131, 2, v131
	s_waitcnt vmcnt(2)
	v_pk_mul_f32 v[146:147], v[18:19], v[150:151]
	v_pk_mul_f32 v[158:159], v[16:17], v[148:149]
	v_mov_b32_e32 v160, v148
	v_mov_b32_e32 v161, v151
	v_mov_b32_e32 v148, v149
	v_mov_b32_e32 v149, v150
	v_mov_b32_e32 v150, v158
	v_mov_b32_e32 v151, v146
	v_mov_b32_e32 v146, v159
	v_pk_mul_f32 v[148:149], v[156:157], v[148:149]
	v_pk_add_f32 v[146:147], v[150:151], v[146:147] neg_lo:[0,1] neg_hi:[0,1]
	v_pk_fma_f32 v[148:149], v[154:155], v[160:161], v[148:149]
	v_pk_mul_f32 v[146:147], v[146:147], s[24:25] op_sel_hi:[1,0]
	v_pk_mul_f32 v[148:149], v[148:149], s[24:25] op_sel_hi:[1,0]
	v_cvt_pk_bf16_f32 v146, v146, v147
	v_cvt_pk_bf16_f32 v147, v148, v149
	v_mov_b32_e32 v216, v146
	v_mov_b32_e32 v217, v147
	global_load_dwordx4 v[146:149], v162, s[16:17]
	global_store_dword v[152:153], v216, off offset:16
	global_store_dword v[152:153], v217, off offset:80
	v_add_u32_e32 v150, 0xffffe0b0, v143
	v_mov_b32_e32 v151, v129
	v_lshrrev_b32_e32 v150, 5, v150
	v_lshlrev_b64 v[150:151], 8, v[150:151]
	v_or_b32_e32 v150, v150, v144
	v_lshl_add_u64 v[144:145], v[150:151], 0, s[28:29]
	v_mad_u64_u32 v[156:157], s[28:29], v144, s57, v[138:139]
	v_mad_i32_i24 v157, v145, s57, v157
	v_lshl_add_u64 v[144:145], v[140:141], 0, s[6:7]
	v_lshl_add_u64 v[156:157], v[156:157], 0, s[22:23]
	v_cndmask_b32_e32 v145, v157, v145, vcc
	v_cndmask_b32_e32 v144, v156, v144, vcc
	v_lshl_add_u64 v[156:157], v[144:145], 0, v[136:137]
	v_mov_b32_e32 v154, v12
	v_mov_b32_e32 v155, v15
	v_mov_b32_e32 v152, v13
	v_mov_b32_e32 v153, v14
	v_lshl_add_u64 v[150:151], v[150:151], 0, s[36:37]
	v_mad_u64_u32 v[138:139], s[28:29], v150, s57, v[138:139]
	v_mad_i32_i24 v139, v151, s57, v139
	v_lshl_add_u64 v[140:141], v[140:141], 0, s[26:27]
	v_lshl_add_u64 v[138:139], v[138:139], 0, s[22:23]
	v_cndmask_b32_e32 v139, v139, v141, vcc
	v_cndmask_b32_e32 v138, v138, v140, vcc
	v_lshl_add_u64 v[140:141], v[138:139], 0, v[136:137]
	s_waitcnt vmcnt(2)
	v_pk_mul_f32 v[144:145], v[14:15], v[148:149]
	v_pk_mul_f32 v[158:159], v[12:13], v[146:147]
	v_mov_b32_e32 v160, v146
	v_mov_b32_e32 v161, v149
	v_mov_b32_e32 v146, v147
	v_mov_b32_e32 v147, v148
	v_mov_b32_e32 v148, v158
	v_mov_b32_e32 v149, v144
	v_mov_b32_e32 v144, v159
	v_pk_mul_f32 v[146:147], v[154:155], v[146:147]
	v_pk_add_f32 v[144:145], v[148:149], v[144:145] neg_lo:[0,1] neg_hi:[0,1]
	v_pk_fma_f32 v[146:147], v[152:153], v[160:161], v[146:147]
	v_pk_mul_f32 v[144:145], v[144:145], s[24:25] op_sel_hi:[1,0]
	v_pk_mul_f32 v[146:147], v[146:147], s[24:25] op_sel_hi:[1,0]
	v_cvt_pk_bf16_f32 v135, v144, v145
	v_cvt_pk_bf16_f32 v144, v146, v147
	v_mov_b32_e32 v216, v135
	v_mov_b32_e32 v217, v144
	global_load_dwordx4 v[144:147], v131, s[16:17]
	global_store_dword v[156:157], v216, off
	global_store_dword v[156:157], v217, off offset:64
	v_mov_b32_e32 v152, v8
	v_mov_b32_e32 v153, v11
	v_mov_b32_e32 v148, v9
	v_mov_b32_e32 v149, v10
	s_waitcnt vmcnt(2)
	v_pk_mul_f32 v[154:155], v[10:11], v[146:147]
	v_pk_mul_f32 v[158:159], v[8:9], v[144:145]
	v_mov_b32_e32 v160, v144
	v_mov_b32_e32 v161, v147
	v_mov_b32_e32 v144, v145
	v_mov_b32_e32 v145, v146
	v_mov_b32_e32 v146, v158
	v_mov_b32_e32 v147, v154
	v_mov_b32_e32 v154, v159
	v_pk_mul_f32 v[144:145], v[152:153], v[144:145]
	v_pk_add_f32 v[146:147], v[146:147], v[154:155] neg_lo:[0,1] neg_hi:[0,1]
	v_pk_fma_f32 v[144:145], v[148:149], v[160:161], v[144:145]
	v_pk_mul_f32 v[146:147], v[146:147], s[24:25] op_sel_hi:[1,0]
	v_pk_mul_f32 v[144:145], v[144:145], s[24:25] op_sel_hi:[1,0]
	v_cvt_pk_bf16_f32 v135, v146, v147
	v_cvt_pk_bf16_f32 v144, v144, v145
	v_mov_b32_e32 v216, v135
	v_mov_b32_e32 v217, v144
	global_load_dwordx4 v[144:147], v162, s[16:17]
	global_store_dword v[156:157], v216, off offset:16
	global_store_dword v[156:157], v217, off offset:80
	v_mov_b32_e32 v152, v4
	v_mov_b32_e32 v153, v7
	v_mov_b32_e32 v148, v5
	v_mov_b32_e32 v149, v6
	s_waitcnt vmcnt(2)
	v_pk_mul_f32 v[136:137], v[6:7], v[146:147]
	v_pk_mul_f32 v[138:139], v[4:5], v[144:145]
	v_mov_b32_e32 v150, v144
	v_mov_b32_e32 v151, v147
	v_mov_b32_e32 v144, v145
	v_mov_b32_e32 v145, v146
	v_mov_b32_e32 v146, v138
	v_mov_b32_e32 v147, v136
	v_mov_b32_e32 v136, v139
	v_pk_mul_f32 v[138:139], v[152:153], v[144:145]
	v_pk_add_f32 v[136:137], v[146:147], v[136:137] neg_lo:[0,1] neg_hi:[0,1]
	v_pk_fma_f32 v[138:139], v[148:149], v[150:151], v[138:139]
	v_pk_mul_f32 v[136:137], v[136:137], s[24:25] op_sel_hi:[1,0]
	v_pk_mul_f32 v[138:139], v[138:139], s[24:25] op_sel_hi:[1,0]
	v_cvt_pk_bf16_f32 v135, v136, v137
	v_cvt_pk_bf16_f32 v136, v138, v139
	v_mov_b32_e32 v216, v135
	v_mov_b32_e32 v217, v136
	global_load_dwordx4 v[136:139], v131, s[16:17]
	global_store_dword v[140:141], v216, off
	global_store_dword v[140:141], v217, off offset:64
	v_mov_b32_e32 v146, v0
	v_mov_b32_e32 v147, v3
	v_mov_b32_e32 v144, v1
	v_mov_b32_e32 v145, v2
	s_waitcnt vmcnt(2)
	v_pk_mul_f32 v[148:149], v[2:3], v[138:139]
	v_pk_mul_f32 v[150:151], v[0:1], v[136:137]
	v_mov_b32_e32 v152, v136
	v_mov_b32_e32 v153, v139
	v_mov_b32_e32 v136, v137
	v_mov_b32_e32 v137, v138
	v_mov_b32_e32 v138, v150
	v_mov_b32_e32 v139, v148
	v_mov_b32_e32 v148, v151
	v_pk_mul_f32 v[136:137], v[146:147], v[136:137]
	v_pk_add_f32 v[138:139], v[138:139], v[148:149] neg_lo:[0,1] neg_hi:[0,1]
	v_pk_fma_f32 v[136:137], v[144:145], v[152:153], v[136:137]
	v_pk_mul_f32 v[138:139], v[138:139], s[24:25] op_sel_hi:[1,0]
	v_pk_mul_f32 v[136:137], v[136:137], s[24:25] op_sel_hi:[1,0]
	v_cvt_pk_bf16_f32 v131, v138, v139
	v_cvt_pk_bf16_f32 v135, v136, v137
	global_store_dword v[140:141], v131, off offset:16
	global_store_dword v[140:141], v135, off offset:80
	s_cbranch_execnz .LBB0_657
	s_branch .LBB0_665
